# baseline (speedup 1.0000x reference)
; #define LAS __attribute__((address_space(3)))
; template <int MODE, bool XF32>
; __device__ __forceinline__ void norm_load(f32x4 (&xf)[8], v4u (&xb)[4], v4u (&tv)[4], int row, const float* xp, const float* xs, const bf16* xb_in, const bf16* XN, int lane) {
;     ...
;         const float* xr = (row < MP ? xp + (size_t)row * DM : xs + (size_t)(row - MP) * DM) + lane * 8;
; #pragma unroll
;         for (int j = 0; j < 4; ++j) { xf[2 * j] = __builtin_nontemporal_load((const f32x4*)(xr + j * 512)); xf[2 * j + 1] = __builtin_nontemporal_load((const f32x4*)(xr + j * 512 + 4)); }
;     }
; template <int MODE, bool XF32>
; __device__ __forceinline__ void norm_phase(LAS unsigned char* lds, const float* xp, const float* xs, const bf16* xb_in, float* xo_f32, bf16* xo_bf16, bf16* XN, const bf16* parts, const float* gpost, const float* gnext, int gw, int NGW, int tid, int lane) {
;     LAS float* gl = (LAS float*)lds;
;     __syncthreads();
;     for (int i = tid; i < DM; i += NTHREADS) { if (MODE == 1) gl[i] = gpost[i]; if (gnext) gl[DM + i] = gnext[i]; }
;     __syncthreads();
.LBB0_19:
	s_load_dwordx4 s[44:47], s[0:1], 0x0
	s_load_dwordx2 s[8:9], s[0:1], 0x28
	s_movk_i32 s4, 0x800
	v_cmp_gt_i32_e32 vcc, s4, v180
	s_waitcnt lgkmcnt(0)
	s_barrier
	s_and_saveexec_b64 s[10:11], vcc
	s_cbranch_execz .LBB0_24
	s_cmp_lg_u64 s[8:9], 0
	s_cselect_b64 s[16:17], -1, 0
	v_ashrrev_i32_e32 v181, 31, v180
	s_add_i32 s4, 0, 0x2000
	s_mov_b64 s[14:15], 0
	v_add_u32_e32 v0, 0xfffffe00, v180
	v_lshl_add_u64 v[2:3], v[180:181], 2, s[8:9]
	v_lshl_add_u32 v4, v180, 2, s4
	s_andn2_b64 vcc, exec, s[16:17]
	s_cbranch_vccnz .Lgain_0
	v_lshl_add_u64 v[244:245], v[2:3], 0, s[94:95]
	v_lshl_add_u64 v[244:245], v[244:245], 0, s[94:95]
	global_load_dword v246, v[2:3], off
	global_load_dword v247, v[2:3], off offset:2048
	global_load_dword v248, v[244:245], off
	global_load_dword v249, v[244:245], off offset:2048
	s_waitcnt vmcnt(0)
	ds_write_b32 v4, v246
	ds_write_b32 v4, v247 offset:2048
	ds_write_b32 v4, v248 offset:4096
	ds_write_b32 v4, v249 offset:6144
.Lgain_0:
.LBB0_24:
	s_or_b64 exec, exec, s[10:11]
	s_cmpk_lt_i32 s6, 0x4800
	s_mov_b64 s[16:17], 0x1000
	s_waitcnt lgkmcnt(0)
	s_barrier
	s_cbranch_scc0 .LBB0_36
	s_cmp_lg_u64 s[8:9], 0
	s_cselect_b64 s[8:9], -1, 0
	s_add_i32 s4, s6, 0xffffc000
	s_ashr_i32 s5, s6, 31
	s_cmpk_lt_i32 s6, 0x4000
	s_cselect_b32 s5, s5, 0
	s_cselect_b32 s4, s6, s4
	s_cselect_b32 s7, s45, s47
	s_cselect_b32 s10, s44, s46
	s_lshl_b64 s[4:5], s[4:5], 13
	s_add_u32 s4, s10, s4
	s_addc_u32 s5, s7, s5
	v_lshlrev_b32_e32 v0, 5, v206
	v_lshl_add_u64 v[26:27], s[4:5], 0, v[0:1]
	global_load_dwordx4 v[2:5], v0, s[4:5] nt
	global_load_dwordx4 v[6:9], v0, s[4:5] offset:16 nt
	global_load_dwordx4 v[10:13], v0, s[4:5] offset:2048 nt
	global_load_dwordx4 v[14:17], v0, s[4:5] offset:2064 nt
	v_add_co_u32_e32 v28, vcc, s80, v26
	v_lshl_add_u64 v[22:23], v[26:27], 0, s[16:17]
	s_nop 0
	v_addc_co_u32_e32 v29, vcc, 0, v27, vcc
	global_load_dwordx4 v[18:21], v[28:29], off nt
	s_nop 0
	global_load_dwordx4 v[22:25], v[22:23], off offset:16 nt
	v_lshl_add_u64 v[26:27], v[26:27], 0, s[34:35]
	global_load_dwordx4 v[34:37], v[28:29], off offset:2048 nt
	global_load_dwordx4 v[46:49], v[26:27], off offset:16 nt
	v_readlane_b32 s4, v240, 2
	v_add_u32_e32 v67, 0, v0
	v_lshlrev_b32_e32 v0, 4, v206
	v_readlane_b32 s5, v240, 3
	s_nop 1
	v_lshl_add_u64 v[68:69], s[4:5], 0, v[0:1]
	s_lshl_b32 s4, s3, 4
	s_branch .LBB0_27

; #define LAS __attribute__((address_space(3)))
; template <int MODE, bool XF32>
; __device__ __forceinline__ void norm_phase(LAS unsigned char* lds, const float* xp, const float* xs, const bf16* xb_in, float* xo_f32, bf16* xo_bf16, bf16* XN, const bf16* parts, const float* gpost, const float* gnext, int gw, int NGW, int tid, int lane) {
;     LAS float* gl = (LAS float*)lds;
;     __syncthreads();
;     for (int i = tid; i < DM; i += NTHREADS) { if (MODE == 1) gl[i] = gpost[i]; if (gnext) gl[DM + i] = gnext[i]; }
;     __syncthreads();
; __global__ void __launch_bounds__(NTHREADS, 2) hymba_fwd(Args a_unused) {
;     ...
;             bf16* Xa = (bf16*)X; bf16* Xb = (bf16*)(ws + WS_W);
;             const bool first = (l == 0 && k == 3), last = (l == 1 && k == 6);
;             const bf16* xin = first ? nullptr : (last ? Xb : Xa);
;             bf16* xob = last ? nullptr : ((l == 1 && k == 3) ? Xb : Xa);
;             const float* gpost = (k == 3 ? a->g_mix_post : a->g_ffn_post) + l * DM;
;             const float* gnext = k == 3 ? a->g_ffn_pre + l * DM : (l == 0 ? a->g_mix_pre + DM : nullptr);
.LBB0_222:
	s_xor_b64 s[4:5], s[18:19], -1
	s_and_b64 s[24:25], s[28:29], s[4:5]
	v_readlane_b32 s4, v240, 6
	s_cmp_eq_u32 s4, 6
	s_load_dwordx2 s[22:23], s[22:23], 0x0
	s_cselect_b64 s[4:5], -1, 0
	s_and_b64 s[26:27], s[18:19], s[4:5]
	s_and_b64 s[4:5], s[18:19], s[28:29]
	s_and_b64 s[4:5], s[4:5], exec
	s_cselect_b32 s7, s86, s57
	s_cselect_b32 s12, s93, s56
	s_and_b64 s[4:5], s[26:27], exec
	s_cselect_b32 s18, 0, s12
	s_cselect_b32 s19, 0, s7
	s_andn2_b64 vcc, exec, s[24:25]
	s_mov_b64 s[28:29], -1
	s_cbranch_vccz .LBB0_280
	s_movk_i32 s4, 0x800
	v_cmp_gt_i32_e32 vcc, s4, v180
	s_waitcnt lgkmcnt(0)
	s_barrier
	s_and_saveexec_b64 s[28:29], vcc
	s_cbranch_execz .LBB0_228
	s_cmp_lg_u64 s[20:21], 0
	s_cselect_b64 s[34:35], -1, 0
	s_lshl_b32 s4, s11, 2
	v_ashrrev_i32_e32 v181, 31, v180
	s_add_u32 s4, s22, s4
	s_waitcnt vmcnt(0)
	v_lshlrev_b64 v[4:5], 2, v[180:181]
	s_addc_u32 s5, s23, 0
	s_mov_b64 s[30:31], 0
	v_add_u32_e32 v0, 0xfffffe00, v180
	v_lshl_add_u32 v6, v180, 2, 0
	v_lshl_add_u64 v[2:3], s[4:5], 0, v[4:5]
	v_lshl_add_u64 v[4:5], s[20:21], 0, v[4:5]
	v_lshl_add_u64 v[244:245], v[2:3], 0, s[94:95]
	v_lshl_add_u64 v[244:245], v[244:245], 0, s[94:95]
	global_load_dword v246, v[2:3], off
	global_load_dword v247, v[2:3], off offset:2048
	global_load_dword v248, v[244:245], off
	global_load_dword v249, v[244:245], off offset:2048
	s_and_b64 vcc, exec, s[34:35]
	s_cbranch_vccz .Lgain_a
	v_lshl_add_u64 v[244:245], v[4:5], 0, s[94:95]
	v_lshl_add_u64 v[244:245], v[244:245], 0, s[94:95]
	global_load_dword v250, v[4:5], off
	global_load_dword v251, v[4:5], off offset:2048
	global_load_dword v252, v[244:245], off
	global_load_dword v253, v[244:245], off offset:2048
	s_waitcnt vmcnt(0)
	ds_write_b32 v6, v250 offset:8192
	ds_write_b32 v6, v251 offset:10240
	ds_write_b32 v6, v252 offset:12288
	ds_write_b32 v6, v253 offset:14336
.Lgain_a:
	s_waitcnt vmcnt(0)
	ds_write_b32 v6, v246
	ds_write_b32 v6, v247 offset:2048
	ds_write_b32 v6, v248 offset:4096
	ds_write_b32 v6, v249 offset:6144

; #define LAS __attribute__((address_space(3)))
; template <int MODE, bool XF32>
; __device__ __forceinline__ void norm_phase(LAS unsigned char* lds, const float* xp, const float* xs, const bf16* xb_in, float* xo_f32, bf16* xo_bf16, bf16* XN, const bf16* parts, const float* gpost, const float* gnext, int gw, int NGW, int tid, int lane) {
;     LAS float* gl = (LAS float*)lds;
;     __syncthreads();
;     for (int i = tid; i < DM; i += NTHREADS) { if (MODE == 1) gl[i] = gpost[i]; if (gnext) gl[DM + i] = gnext[i]; }
;     __syncthreads();
.LBB0_280:
	s_and_b64 vcc, exec, s[28:29]
	s_cbranch_vccz .LBB0_321
	s_load_dwordx4 s[48:51], s[0:1], 0x0
	s_movk_i32 s4, 0x800
	v_cmp_gt_i32_e32 vcc, s4, v180
	s_waitcnt lgkmcnt(0)
	s_barrier
	s_and_saveexec_b64 s[24:25], vcc
	s_cbranch_execz .LBB0_286
	s_cmp_lg_u64 s[20:21], 0
	s_cselect_b64 s[28:29], -1, 0
	s_lshl_b32 s4, s11, 2
	v_ashrrev_i32_e32 v181, 31, v180
	s_add_u32 s4, s22, s4
	s_waitcnt vmcnt(0)
	v_lshlrev_b64 v[4:5], 2, v[180:181]
	s_addc_u32 s5, s23, 0
	s_mov_b64 s[26:27], 0
	v_add_u32_e32 v0, 0xfffffe00, v180
	v_lshl_add_u32 v6, v180, 2, 0
	v_lshl_add_u64 v[2:3], s[4:5], 0, v[4:5]
	v_lshl_add_u64 v[4:5], s[20:21], 0, v[4:5]
	v_lshl_add_u64 v[244:245], v[2:3], 0, s[94:95]
	v_lshl_add_u64 v[244:245], v[244:245], 0, s[94:95]
	global_load_dword v246, v[2:3], off
	global_load_dword v247, v[2:3], off offset:2048
	global_load_dword v248, v[244:245], off
	global_load_dword v249, v[244:245], off offset:2048
	s_and_b64 vcc, exec, s[28:29]
	s_cbranch_vccz .Lgain_b
	v_lshl_add_u64 v[244:245], v[4:5], 0, s[94:95]
	v_lshl_add_u64 v[244:245], v[244:245], 0, s[94:95]
	global_load_dword v250, v[4:5], off
	global_load_dword v251, v[4:5], off offset:2048
	global_load_dword v252, v[244:245], off
	global_load_dword v253, v[244:245], off offset:2048
	s_waitcnt vmcnt(0)
	ds_write_b32 v6, v250 offset:8192
	ds_write_b32 v6, v251 offset:10240
	ds_write_b32 v6, v252 offset:12288
	ds_write_b32 v6, v253 offset:14336
